# v51: v45 + HGRN unit 64 bf16 scalars loaded with global_load_short_d16_hi (shift dropped, consumer reads load reg, regs zeroed once), 4 trans-use nops
# baseline (speedup 1.0000x reference)
; #define HM_LOAD(RQ, RZ, RV, j_) do { _Pragma("unroll") for (int i = 0; i < 16; ++i) { const bf16_t* pr_ = proj + HM_TOK((j_) * 16 + i) * INW; RQ[i] = pr_[qc]; RZ[i] = pr_[zc]; RV[i] = pr_[vc]; } } while (0)
; __device__ __forceinline__ void hgrn_mfma_unit(const Params& P, int l, LAS unsigned char* lds, int b, int half) {
;     ...
;         const float lb = ((const float*)(P.ws + WS_CTL))[CW_LB + ((size_t)dir * DEPTH + l) * 256 + h * 64 + lane];
;         const float oml = 1.0f - lb;
;         const int qc = PB_Q + h * 64 + lane, zc = (dir ? PB_FB : PB_FF) + h * 64 + lane, vc = PB_I + h * 64 + lane;
;         const size_t tb = (size_t)b * TT;
;     ...
;         unsigned aq[16], az[16], av[16], bq[16], bz[16], bv[16];
;         HM_LOAD(aq, az, av, 0); HM_LOAD(bq, bz, bv, 1);
.LBB0_461:
	s_andn2_b64 vcc, exec, s[10:11]
	s_cbranch_vccnz .LBB0_719
	v_mov_b32_e32 v8, v200
	v_mov_b32_e32 v202, 0x358637bd
	v_ashrrev_i32_e32 v0, 6, v8
	v_mov_b32_e32 v201, 1
	v_mov_b32_e32 v203, 0x400
	v_cmp_gt_i32_e32 vcc, 4, v0
	s_and_saveexec_b64 s[10:11], vcc
	s_cbranch_execz .LBB0_718
	v_and_b32_e32 v5, 1, v0
	s_mov_b32 s9, 0x2400000
	v_mul_lo_u32 v128, v5, s9
	s_movk_i32 s9, 0x2300
	v_mul_lo_u32 v11, v0, s9
	s_lshl_b32 s9, s37, 7
	s_and_b32 s9, s9, 0x80
	v_bfe_i32 v4, v0, 0, 1
	v_lshl_add_u32 v0, v0, 5, s9
	v_and_b32_e32 v130, 0xffffffc0, v0
	v_readlane_b32 s18, v255, 24
	v_ashrrev_i32_e32 v131, 31, v130
	v_lshlrev_b32_e32 v0, 12, v5
	v_mov_b32_e32 v1, v129
	v_readlane_b32 s19, v255, 25
	v_and_b32_e32 v9, 63, v8
	v_lshlrev_b32_e32 v132, 2, v9
	v_lshl_add_u64 v[2:3], s[18:19], 0, v[0:1]
	v_lshlrev_b64 v[0:1], 2, v[130:131]
	v_lshl_add_u64 v[2:3], v[2:3], 0, v[0:1]
	v_mov_b32_e32 v133, v129
	v_lshl_add_u64 v[2:3], v[2:3], 0, v[132:133]
	s_movk_i32 s13, 0x2000
	v_add_co_u32_e32 v6, vcc, s13, v2
	s_add_i32 s8, s37, 0xffffff80
	s_nop 0
	v_addc_co_u32_e32 v7, vcc, 0, v3, vcc
	v_cmp_eq_u32_e32 vcc, 0, v5
	v_mov_b32_e32 v2, 0x500
	s_lshr_b32 s12, s8, 1
	v_cndmask_b32_e32 v2, v2, v203, vcc
	v_mov_b32_e32 v16, 0xfe
	v_bfrev_b32_e32 v20, -0.5
	v_add_u32_e32 v2, v2, v130
	s_mul_i32 s64, s12, 0x900
	v_cndmask_b32_e64 v16, v16, 1, vcc
	v_cndmask_b32_e64 v20, v20, 2, vcc
	v_or_b32_e32 v134, v2, v9
	v_or_b32_sdwa v2, v4, s64 dst_sel:DWORD dst_unused:UNUSED_PAD src0_sel:BYTE_0 src1_sel:DWORD
	s_movk_i32 s12, 0xb00
	v_or_b32_e32 v16, s64, v16
	v_or_b32_e32 v20, s64, v20
	v_ashrrev_i32_e32 v135, 31, v134
	v_mul_lo_u32 v2, v2, s12
	v_mov_b32_e32 v3, v129
	v_or_b32_e32 v130, v130, v9
	v_mul_lo_u32 v16, v16, s12
	v_mov_b32_e32 v17, v129
	v_mul_lo_u32 v20, v20, s12
	v_mov_b32_e32 v21, v129
	v_cmp_eq_u32_e64 s[38:39], 1, v5
	v_lshl_add_u64 v[12:13], v[2:3], 1, s[56:57]
	v_lshlrev_b64 v[4:5], 1, v[130:131]
	v_lshlrev_b64 v[2:3], 1, v[134:135]
	v_lshl_add_u64 v[16:17], v[16:17], 1, s[56:57]
	v_lshl_add_u64 v[20:21], v[20:21], 1, s[56:57]
	v_lshl_add_u64 v[14:15], v[12:13], 0, v[4:5]
	v_lshl_add_u64 v[12:13], v[12:13], 0, v[2:3]
	v_lshl_add_u64 v[18:19], v[16:17], 0, v[4:5]
	v_lshl_add_u64 v[16:17], v[16:17], 0, v[2:3]
	v_lshl_add_u64 v[22:23], v[20:21], 0, v[4:5]
	global_load_dword v24, v[6:7], off
	v_mov_b32_e32 v147, 0
	v_mov_b32_e32 v148, 0
	v_mov_b32_e32 v149, 0
	v_mov_b32_e32 v150, 0
	v_mov_b32_e32 v151, 0
	v_mov_b32_e32 v154, 0
	v_mov_b32_e32 v155, 0
	v_mov_b32_e32 v156, 0
	v_mov_b32_e32 v157, 0
	v_mov_b32_e32 v158, 0
	v_mov_b32_e32 v162, 0
	v_mov_b32_e32 v163, 0
	v_mov_b32_e32 v164, 0
	v_mov_b32_e32 v165, 0
	v_mov_b32_e32 v166, 0
	v_mov_b32_e32 v170, 0
	v_mov_b32_e32 v171, 0
	v_mov_b32_e32 v172, 0
	v_mov_b32_e32 v173, 0
	v_mov_b32_e32 v174, 0
	v_mov_b32_e32 v175, 0
	v_mov_b32_e32 v178, 0
	v_mov_b32_e32 v186, 0
	v_mov_b32_e32 v187, 0
	v_mov_b32_e32 v188, 0
	v_mov_b32_e32 v189, 0
	v_mov_b32_e32 v190, 0
	v_mov_b32_e32 v194, 0
	v_mov_b32_e32 v195, 0
	v_mov_b32_e32 v196, 0
	v_mov_b32_e32 v197, 0
	v_mov_b32_e32 v198, 0
	v_mov_b32_e32 v204, 0
	v_mov_b32_e32 v205, 0
	v_mov_b32_e32 v206, 0
	v_mov_b32_e32 v211, 0
	v_mov_b32_e32 v212, 0
	v_mov_b32_e32 v213, 0
	v_mov_b32_e32 v214, 0
	v_mov_b32_e32 v215, 0
	v_mov_b32_e32 v216, 0
	v_mov_b32_e32 v219, 0
	v_mov_b32_e32 v220, 0
	v_mov_b32_e32 v221, 0
	v_mov_b32_e32 v222, 0
	v_mov_b32_e32 v224, 0
	v_mov_b32_e32 v227, 0
	v_mov_b32_e32 v228, 0
	v_mov_b32_e32 v229, 0
	v_mov_b32_e32 v230, 0
	v_mov_b32_e32 v231, 0
	v_mov_b32_e32 v235, 0
	v_mov_b32_e32 v236, 0
	v_mov_b32_e32 v237, 0
	v_mov_b32_e32 v238, 0
	v_mov_b32_e32 v239, 0
	v_mov_b32_e32 v240, 0
	v_mov_b32_e32 v243, 0
	v_mov_b32_e32 v244, 0
	v_mov_b32_e32 v245, 0
	v_mov_b32_e32 v246, 0
	v_mov_b32_e32 v248, 0
	v_mov_b32_e32 v251, 0
	v_mov_b32_e32 v252, 0
	global_load_short_d16_hi v149, v[14:15], off offset:1536
	global_load_short_d16_hi v151, v[12:13], off
	global_load_short_d16_hi v148, v[18:19], off offset:1536
	global_load_short_d16_hi v150, v[16:17], off
	global_load_short_d16_hi v147, v[22:23], off offset:1536
	global_load_ushort v152, v[18:19], off offset:3072
	global_load_ushort v153, v[14:15], off offset:3072
	v_bfrev_b32_e32 v12, 0.5
	v_mov_b32_e32 v16, 0xfb
	v_cndmask_b32_e64 v12, v12, 3, vcc
	v_cndmask_b32_e64 v16, v16, 4, vcc
	v_or_b32_e32 v12, s64, v12
	v_or_b32_e32 v16, s64, v16
	v_mul_lo_u32 v12, v12, s12
	v_mov_b32_e32 v13, v129
	v_mul_lo_u32 v16, v16, s12
	v_mov_b32_e32 v17, v129
	v_lshl_add_u64 v[6:7], v[20:21], 0, v[2:3]
	v_lshl_add_u64 v[12:13], v[12:13], 1, s[56:57]
	v_lshl_add_u64 v[16:17], v[16:17], 1, s[56:57]
	v_lshl_add_u64 v[14:15], v[12:13], 0, v[4:5]
	v_lshl_add_u64 v[12:13], v[12:13], 0, v[2:3]
	v_lshl_add_u64 v[18:19], v[16:17], 0, v[4:5]
	v_lshl_add_u64 v[16:17], v[16:17], 0, v[2:3]
	global_load_short_d16_hi v158, v[6:7], off
	global_load_short_d16_hi v155, v[14:15], off offset:1536
	global_load_short_d16_hi v157, v[12:13], off
	global_load_short_d16_hi v154, v[18:19], off offset:1536
	global_load_short_d16_hi v156, v[16:17], off
	global_load_ushort v159, v[18:19], off offset:3072
	global_load_ushort v160, v[14:15], off offset:3072
	global_load_ushort v161, v[22:23], off offset:3072
	v_mov_b32_e32 v6, 0xfa
	v_cndmask_b32_e64 v6, v6, 5, vcc
	v_mov_b32_e32 v14, 0xf9
	v_mov_b32_e32 v18, 0xf8
	v_or_b32_e32 v6, s64, v6
	v_cndmask_b32_e64 v14, v14, 6, vcc
	v_cndmask_b32_e64 v18, v18, 7, vcc
	v_mul_lo_u32 v6, v6, s12
	v_mov_b32_e32 v7, v129
	v_or_b32_e32 v14, s64, v14
	v_or_b32_e32 v18, s64, v18
	v_lshl_add_u64 v[6:7], v[6:7], 1, s[56:57]
	v_mul_lo_u32 v14, v14, s12
	v_mov_b32_e32 v15, v129
	v_mul_lo_u32 v18, v18, s12
	v_mov_b32_e32 v19, v129
; #define HM_LOAD(RQ, RZ, RV, j_) do { _Pragma("unroll") for (int i = 0; i < 16; ++i) { const bf16_t* pr_ = proj + HM_TOK((j_) * 16 + i) * INW; RQ[i] = pr_[qc]; RZ[i] = pr_[zc]; RV[i] = pr_[vc]; } } while (0)
; __device__ __forceinline__ void hgrn_mfma_unit(const Params& P, int l, LAS unsigned char* lds, int b, int half) {
;     ...
;         unsigned aq[16], az[16], av[16], bq[16], bz[16], bv[16];
;         HM_LOAD(aq, az, av, 0); HM_LOAD(bq, bz, bv, 1);
	v_lshl_add_u64 v[12:13], v[6:7], 0, v[4:5]
	v_lshl_add_u64 v[14:15], v[14:15], 1, s[56:57]
	v_lshl_add_u64 v[18:19], v[18:19], 1, s[56:57]
	v_lshl_add_u64 v[6:7], v[6:7], 0, v[2:3]
	v_lshl_add_u64 v[16:17], v[14:15], 0, v[4:5]
	v_lshl_add_u64 v[14:15], v[14:15], 0, v[2:3]
	v_lshl_add_u64 v[20:21], v[18:19], 0, v[4:5]
	global_load_short_d16_hi v164, v[12:13], off offset:1536
	global_load_short_d16_hi v166, v[6:7], off
	global_load_short_d16_hi v163, v[16:17], off offset:1536
	global_load_short_d16_hi v165, v[14:15], off
	global_load_short_d16_hi v162, v[20:21], off offset:1536
	global_load_ushort v167, v[20:21], off offset:3072
	global_load_ushort v168, v[16:17], off offset:3072
	global_load_ushort v169, v[12:13], off offset:3072
	v_mov_b32_e32 v12, 0xf7
	v_cndmask_b32_e64 v12, v12, 8, vcc
	v_mov_b32_e32 v16, 0xf6
	v_mov_b32_e32 v20, 0xf5
	v_or_b32_e32 v12, s64, v12
	v_cndmask_b32_e64 v16, v16, 9, vcc
	v_cndmask_b32_e64 v20, v20, 10, vcc
	v_mul_lo_u32 v12, v12, s12
	v_mov_b32_e32 v13, v129
	v_or_b32_e32 v16, s64, v16
	v_or_b32_e32 v20, s64, v20
	v_lshl_add_u64 v[12:13], v[12:13], 1, s[56:57]
	v_mul_lo_u32 v16, v16, s12
	v_mov_b32_e32 v17, v129
	v_mul_lo_u32 v20, v20, s12
	v_mov_b32_e32 v21, v129
	v_lshl_add_u64 v[6:7], v[18:19], 0, v[2:3]
	v_lshl_add_u64 v[14:15], v[12:13], 0, v[4:5]
	v_lshl_add_u64 v[12:13], v[12:13], 0, v[2:3]
	v_lshl_add_u64 v[16:17], v[16:17], 1, s[56:57]
	v_lshl_add_u64 v[20:21], v[20:21], 1, s[56:57]
	v_lshl_add_u64 v[18:19], v[16:17], 0, v[4:5]
	v_lshl_add_u64 v[16:17], v[16:17], 0, v[2:3]
	v_lshl_add_u64 v[22:23], v[20:21], 0, v[4:5]
	global_load_short_d16_hi v175, v[6:7], off
	global_load_short_d16_hi v172, v[14:15], off offset:1536
	global_load_short_d16_hi v174, v[12:13], off
	global_load_short_d16_hi v171, v[18:19], off offset:1536
	global_load_short_d16_hi v173, v[16:17], off
	global_load_short_d16_hi v170, v[22:23], off offset:1536
	global_load_ushort v176, v[18:19], off offset:3072
	global_load_ushort v177, v[14:15], off offset:3072
	v_mov_b32_e32 v12, 0xf4
	v_cndmask_b32_e64 v12, v12, 11, vcc
	v_mov_b32_e32 v16, 0xf3
	v_or_b32_e32 v12, s64, v12
	v_cndmask_b32_e64 v16, v16, 12, vcc
	v_mul_lo_u32 v12, v12, s12
	v_mov_b32_e32 v13, v129
	v_or_b32_e32 v16, s64, v16
	v_lshl_add_u64 v[12:13], v[12:13], 1, s[56:57]
	v_mul_lo_u32 v16, v16, s12
	v_mov_b32_e32 v17, v129
	v_lshl_add_u64 v[6:7], v[20:21], 0, v[2:3]
	v_lshl_add_u64 v[14:15], v[12:13], 0, v[4:5]
	v_lshl_add_u64 v[16:17], v[16:17], 1, s[56:57]
	v_lshl_add_u64 v[12:13], v[12:13], 0, v[2:3]
	v_lshl_add_u64 v[18:19], v[16:17], 0, v[4:5]
	v_lshl_add_u64 v[16:17], v[16:17], 0, v[2:3]
	global_load_short_d16_hi v190, v[6:7], off
	global_load_short_d16_hi v187, v[14:15], off offset:1536
	global_load_short_d16_hi v189, v[12:13], off
	global_load_short_d16_hi v186, v[18:19], off offset:1536
	global_load_short_d16_hi v188, v[16:17], off
	global_load_ushort v191, v[18:19], off offset:3072
	global_load_ushort v192, v[14:15], off offset:3072
	global_load_ushort v193, v[22:23], off offset:3072
	v_mov_b32_e32 v6, 0xf2
	v_mov_b32_e32 v14, 0xf1
	v_cndmask_b32_e64 v6, v6, 13, vcc
	v_cndmask_b32_e64 v14, v14, 14, vcc
	v_mov_b32_e32 v18, 0xf0
	v_or_b32_e32 v6, s64, v6
	v_or_b32_e32 v14, s64, v14
	v_cndmask_b32_e64 v18, v18, 15, vcc
	v_mul_lo_u32 v6, v6, s12
	v_mov_b32_e32 v7, v129
	v_mul_lo_u32 v14, v14, s12
	v_mov_b32_e32 v15, v129
	v_or_b32_e32 v18, s64, v18
	v_lshl_add_u64 v[6:7], v[6:7], 1, s[56:57]
	v_lshl_add_u64 v[14:15], v[14:15], 1, s[56:57]
	v_mul_lo_u32 v18, v18, s12
	v_mov_b32_e32 v19, v129
	v_lshl_add_u64 v[12:13], v[6:7], 0, v[4:5]
	v_lshl_add_u64 v[16:17], v[14:15], 0, v[4:5]
	v_lshl_add_u64 v[14:15], v[14:15], 0, v[2:3]
	v_lshl_add_u64 v[18:19], v[18:19], 1, s[56:57]
	v_lshl_add_u64 v[6:7], v[6:7], 0, v[2:3]
	v_lshl_add_u64 v[20:21], v[18:19], 0, v[4:5]
	global_load_short_d16_hi v196, v[12:13], off offset:1536
	global_load_short_d16_hi v198, v[6:7], off
	global_load_short_d16_hi v195, v[16:17], off offset:1536
	global_load_short_d16_hi v197, v[14:15], off
	global_load_short_d16_hi v194, v[20:21], off offset:1536
	global_load_ushort v199, v[20:21], off offset:3072
	global_load_ushort v209, v[16:17], off offset:3072
	global_load_ushort v210, v[12:13], off offset:3072
	v_mov_b32_e32 v14, 0xef
	v_lshl_add_u64 v[12:13], v[18:19], 0, v[2:3]
	v_readlane_b32 s12, v255, 26
	v_cndmask_b32_e64 v14, v14, 16, vcc
	v_mov_b32_e32 v18, 0xee
	v_readlane_b32 s13, v255, 27
	v_or_b32_e32 v14, s64, v14
	v_cndmask_b32_e64 v18, v18, 17, vcc
	v_mov_b32_e32 v22, 0xed
	v_lshl_add_u64 v[6:7], s[12:13], 0, v[128:129]
	v_mul_lo_u32 v128, v14, s23
	v_or_b32_e32 v18, s64, v18
	v_cndmask_b32_e64 v22, v22, 18, vcc
	v_lshl_add_u64 v[14:15], s[56:57], 0, v[128:129]
	v_mul_lo_u32 v128, v18, s23
	v_or_b32_e32 v22, s64, v22
	v_lshl_add_u64 v[18:19], s[56:57], 0, v[128:129]
	v_mul_lo_u32 v128, v22, s23
	v_lshl_add_u64 v[16:17], v[14:15], 0, v[4:5]
	v_lshl_add_u64 v[14:15], v[14:15], 0, v[2:3]
	v_lshl_add_u64 v[22:23], s[56:57], 0, v[128:129]
	s_waitcnt vmcnt(47)
; #define HM_LOAD(RQ, RZ, RV, j_) do { _Pragma("unroll") for (int i = 0; i < 16; ++i) { const bf16_t* pr_ = proj + HM_TOK((j_) * 16 + i) * INW; RQ[i] = pr_[qc]; RZ[i] = pr_[zc]; RV[i] = pr_[vc]; } } while (0)
; __device__ __forceinline__ void hgrn_mfma_unit(const Params& P, int l, LAS unsigned char* lds, int b, int half) {
;     ...
;         unsigned aq[16], az[16], av[16], bq[16], bz[16], bv[16];
;         HM_LOAD(aq, az, av, 0); HM_LOAD(bq, bz, bv, 1);
	v_sub_f32_e32 v136, 1.0, v24
	v_lshl_add_u64 v[20:21], v[18:19], 0, v[4:5]
	v_lshl_add_u64 v[18:19], v[18:19], 0, v[2:3]
	v_lshl_add_u64 v[24:25], v[22:23], 0, v[4:5]
	global_load_short_d16_hi v211, v[12:13], off
	global_load_short_d16_hi v214, v[16:17], off offset:1536
	global_load_short_d16_hi v216, v[14:15], off
	global_load_short_d16_hi v213, v[20:21], off offset:1536
	global_load_short_d16_hi v215, v[18:19], off
	global_load_short_d16_hi v212, v[24:25], off offset:1536
	global_load_ushort v217, v[20:21], off offset:3072
	global_load_ushort v218, v[16:17], off offset:3072
	v_mov_b32_e32 v14, 0xec
	v_cndmask_b32_e64 v14, v14, 19, vcc
	v_mov_b32_e32 v18, 0xeb
	v_or_b32_e32 v14, s64, v14
	v_cndmask_b32_e64 v18, v18, 20, vcc
	v_mul_lo_u32 v128, v14, s23
	v_or_b32_e32 v18, s64, v18
	v_lshl_add_u64 v[14:15], s[56:57], 0, v[128:129]
	v_mul_lo_u32 v128, v18, s23
	v_lshl_add_u64 v[12:13], v[22:23], 0, v[2:3]
	v_lshl_add_u64 v[18:19], s[56:57], 0, v[128:129]
	v_lshl_add_u64 v[16:17], v[14:15], 0, v[4:5]
	v_lshl_add_u64 v[14:15], v[14:15], 0, v[2:3]
	v_lshl_add_u64 v[20:21], v[18:19], 0, v[4:5]
	v_lshl_add_u64 v[18:19], v[18:19], 0, v[2:3]
	global_load_short_d16_hi v224, v[12:13], off
	global_load_short_d16_hi v220, v[16:17], off offset:1536
	global_load_short_d16_hi v222, v[14:15], off
	global_load_short_d16_hi v219, v[20:21], off offset:1536
	global_load_short_d16_hi v221, v[18:19], off
	global_load_ushort v223, v[20:21], off offset:3072
	global_load_ushort v225, v[16:17], off offset:3072
	global_load_ushort v226, v[24:25], off offset:3072
	v_mov_b32_e32 v12, 0xea
	v_cndmask_b32_e64 v12, v12, 21, vcc
	v_mov_b32_e32 v16, 0xe9
	v_or_b32_e32 v12, s64, v12
	v_cndmask_b32_e64 v16, v16, 22, vcc
	v_mov_b32_e32 v20, 0xe8
	v_mul_lo_u32 v128, v12, s23
	v_or_b32_e32 v16, s64, v16
	v_cndmask_b32_e64 v20, v20, 23, vcc
	v_lshl_add_u64 v[12:13], s[56:57], 0, v[128:129]
	v_mul_lo_u32 v128, v16, s23
	v_or_b32_e32 v20, s64, v20
	v_lshl_add_u64 v[16:17], s[56:57], 0, v[128:129]
	v_mul_lo_u32 v128, v20, s23
	v_lshl_add_u64 v[14:15], v[12:13], 0, v[4:5]
	v_lshl_add_u64 v[20:21], s[56:57], 0, v[128:129]
	v_lshl_add_u64 v[12:13], v[12:13], 0, v[2:3]
	v_lshl_add_u64 v[18:19], v[16:17], 0, v[4:5]
	v_lshl_add_u64 v[16:17], v[16:17], 0, v[2:3]
	v_lshl_add_u64 v[22:23], v[20:21], 0, v[4:5]
	global_load_short_d16_hi v229, v[14:15], off offset:1536
	global_load_short_d16_hi v231, v[12:13], off
	global_load_short_d16_hi v228, v[18:19], off offset:1536
	global_load_short_d16_hi v230, v[16:17], off
	global_load_short_d16_hi v227, v[22:23], off offset:1536
	global_load_ushort v232, v[22:23], off offset:3072
	global_load_ushort v233, v[18:19], off offset:3072
	global_load_ushort v234, v[14:15], off offset:3072
	v_mov_b32_e32 v14, 0xe7
	v_cndmask_b32_e64 v14, v14, 24, vcc
	v_mov_b32_e32 v18, 0xe6
	v_or_b32_e32 v14, s64, v14
	v_cndmask_b32_e64 v18, v18, 25, vcc
	v_mov_b32_e32 v22, 0xe5
	v_mul_lo_u32 v128, v14, s23
	v_or_b32_e32 v18, s64, v18
	v_cndmask_b32_e64 v22, v22, 26, vcc
	v_lshl_add_u64 v[14:15], s[56:57], 0, v[128:129]
	v_mul_lo_u32 v128, v18, s23
	v_or_b32_e32 v22, s64, v22
	v_lshl_add_u64 v[18:19], s[56:57], 0, v[128:129]
	v_mul_lo_u32 v128, v22, s23
	v_lshl_add_u64 v[12:13], v[20:21], 0, v[2:3]
	v_lshl_add_u64 v[16:17], v[14:15], 0, v[4:5]
	v_lshl_add_u64 v[14:15], v[14:15], 0, v[2:3]
	v_lshl_add_u64 v[22:23], s[56:57], 0, v[128:129]
	v_lshl_add_u64 v[20:21], v[18:19], 0, v[4:5]
	v_lshl_add_u64 v[18:19], v[18:19], 0, v[2:3]
	v_lshl_add_u64 v[24:25], v[22:23], 0, v[4:5]
	global_load_short_d16_hi v240, v[12:13], off
	global_load_short_d16_hi v237, v[16:17], off offset:1536
	global_load_short_d16_hi v239, v[14:15], off
	global_load_short_d16_hi v236, v[20:21], off offset:1536
	global_load_short_d16_hi v238, v[18:19], off
	global_load_short_d16_hi v235, v[24:25], off offset:1536
	global_load_ushort v241, v[20:21], off offset:3072
	global_load_ushort v242, v[16:17], off offset:3072
	v_mov_b32_e32 v14, 0xe4
	v_cndmask_b32_e64 v14, v14, 27, vcc
	v_mov_b32_e32 v18, 0xe3
	v_or_b32_e32 v14, s64, v14
	v_cndmask_b32_e64 v18, v18, 28, vcc
	v_mul_lo_u32 v128, v14, s23
	v_or_b32_e32 v18, s64, v18
	v_lshl_add_u64 v[14:15], s[56:57], 0, v[128:129]
	v_mul_lo_u32 v128, v18, s23
; #define HM_LOAD(RQ, RZ, RV, j_) do { _Pragma("unroll") for (int i = 0; i < 16; ++i) { const bf16_t* pr_ = proj + HM_TOK((j_) * 16 + i) * INW; RQ[i] = pr_[qc]; RZ[i] = pr_[zc]; RV[i] = pr_[vc]; } } while (0)
; __device__ __forceinline__ void hgrn_mfma_unit(const Params& P, int l, LAS unsigned char* lds, int b, int half) {
;     ...
;         unsigned aq[16], az[16], av[16], bq[16], bz[16], bv[16];
;         HM_LOAD(aq, az, av, 0); HM_LOAD(bq, bz, bv, 1);
;         f32x4 S[4][4];
; #pragma unroll
;         for (int mb = 0; mb < 4; ++mb)
; #pragma unroll
;             for (int nb = 0; nb < 4; ++nb) S[mb][nb] = (f32x4){0.f, 0.f, 0.f, 0.f};
;         f32x4 o[4];
;         constexpr int NSC = TT / 16;
	v_lshl_add_u64 v[12:13], v[22:23], 0, v[2:3]
	v_lshl_add_u64 v[18:19], s[56:57], 0, v[128:129]
	v_lshl_add_u64 v[16:17], v[14:15], 0, v[4:5]
	v_lshl_add_u64 v[14:15], v[14:15], 0, v[2:3]
	v_lshl_add_u64 v[20:21], v[18:19], 0, v[4:5]
	v_lshl_add_u64 v[18:19], v[18:19], 0, v[2:3]
	global_load_short_d16_hi v248, v[12:13], off
	global_load_short_d16_hi v244, v[16:17], off offset:1536
	global_load_short_d16_hi v246, v[14:15], off
	global_load_short_d16_hi v243, v[20:21], off offset:1536
	global_load_short_d16_hi v245, v[18:19], off
	global_load_ushort v247, v[20:21], off offset:3072
	global_load_ushort v249, v[16:17], off offset:3072
	global_load_ushort v250, v[24:25], off offset:3072
	v_mov_b32_e32 v12, 0xe2
	v_cndmask_b32_e64 v12, v12, 29, vcc
	v_mov_b32_e32 v16, 0xe1
	v_or_b32_e32 v12, s64, v12
	v_cndmask_b32_e64 v16, v16, 30, vcc
	v_mov_b32_e32 v20, 0xe0
	v_mul_lo_u32 v128, v12, s23
	v_or_b32_e32 v16, s64, v16
	v_cndmask_b32_e64 v20, v20, 31, vcc
	v_lshl_add_u64 v[12:13], s[56:57], 0, v[128:129]
	v_mul_lo_u32 v128, v16, s23
	v_or_b32_e32 v20, s64, v20
	v_lshl_add_u64 v[16:17], s[56:57], 0, v[128:129]
	v_mul_lo_u32 v128, v20, s23
	v_lshl_add_u64 v[14:15], v[12:13], 0, v[4:5]
	v_lshl_add_u64 v[20:21], s[56:57], 0, v[128:129]
	v_lshl_add_u64 v[12:13], v[12:13], 0, v[2:3]
	v_lshl_add_u64 v[18:19], v[16:17], 0, v[4:5]
	v_lshl_add_u64 v[16:17], v[16:17], 0, v[2:3]
	v_lshl_add_u64 v[4:5], v[20:21], 0, v[4:5]
	global_load_short_d16_hi v205, v[14:15], off offset:1536
	global_load_short_d16_hi v206, v[12:13], off
	global_load_short_d16_hi v252, v[18:19], off offset:1536
	global_load_short_d16_hi v204, v[16:17], off
	global_load_short_d16_hi v251, v[4:5], off offset:1536
	global_load_ushort v208, v[4:5], off offset:3072
	global_load_ushort v179, v[18:19], off offset:3072
	global_load_ushort v180, v[14:15], off offset:3072
	v_lshl_add_u64 v[2:3], v[20:21], 0, v[2:3]
	global_load_short_d16_hi v178, v[2:3], off
	v_bfe_u32 v10, v8, 4, 2
	v_and_b32_e32 v142, 15, v8
	v_and_b32_e32 v138, 48, v8
	v_lshlrev_b32_e32 v4, 2, v10
	v_lshl_add_u64 v[0:1], v[6:7], 0, v[0:1]
	v_mov_b32_e32 v139, v129
	v_add_u32_e32 v133, 0, v11
	v_lshlrev_b32_e32 v2, 1, v9
	v_lshlrev_b32_e32 v3, 5, v9
	s_movk_i32 s7, 0x90
	v_cmp_gt_u32_e64 s[40:41], v4, v142
	v_cmp_lt_u32_e64 s[42:43], v4, v142
	v_or_b32_e32 v5, 2, v4
	v_or_b32_e32 v4, 3, v4
	v_lshl_add_u64 v[140:141], v[0:1], 0, v[138:139]
	v_mov_b32_e32 v0, 0
	s_mov_b32 s8, 63
	s_mov_b32 s9, 0
	v_mad_u32_u24 v143, v142, s7, v133
	v_cmp_gt_u32_e64 s[44:45], v5, v142
	v_cmp_gt_u32_e64 s[46:47], v4, v142
	v_lshlrev_b32_e32 v144, 3, v10
	v_lshl_add_u32 v145, v142, 5, v133
	v_cmp_gt_u32_e64 s[48:49], 32, v9
	v_mov_b32_e32 v137, v136
	v_add_u32_e32 v139, v133, v2
	v_add_u32_e32 v146, v133, v3
	v_mov_b32_e32 v1, v0
	v_mov_b32_e32 v2, v0
	v_mov_b32_e32 v3, v0
	v_mov_b32_e32 v4, v0
	v_mov_b32_e32 v5, v0
	v_mov_b32_e32 v6, v0
	v_mov_b32_e32 v7, v0
	v_mov_b32_e32 v8, v0
	v_mov_b32_e32 v9, v0
	v_mov_b32_e32 v10, v0
	v_mov_b32_e32 v11, v0
	v_mov_b32_e32 v12, v0
	v_mov_b32_e32 v13, v0
	v_mov_b32_e32 v14, v0
	v_mov_b32_e32 v15, v0
	v_mov_b32_e32 v16, v0
	v_mov_b32_e32 v17, v0
	v_mov_b32_e32 v18, v0
	v_mov_b32_e32 v19, v0
	v_mov_b32_e32 v20, v0
	v_mov_b32_e32 v21, v0
	v_mov_b32_e32 v22, v0
	v_mov_b32_e32 v23, v0
	v_mov_b32_e32 v24, v0
	v_mov_b32_e32 v25, v0
	v_mov_b32_e32 v26, v0
	v_mov_b32_e32 v27, v0
	v_mov_b32_e32 v28, v0
	v_mov_b32_e32 v29, v0
	v_mov_b32_e32 v30, v0
	v_mov_b32_e32 v31, v0
	v_mov_b32_e32 v32, v0
	v_mov_b32_e32 v33, v0
	v_mov_b32_e32 v34, v0
	v_mov_b32_e32 v35, v0
	v_mov_b32_e32 v36, v0
	v_mov_b32_e32 v37, v0
	v_mov_b32_e32 v38, v0
	v_mov_b32_e32 v39, v0
	v_mov_b32_e32 v40, v0
	v_mov_b32_e32 v41, v0
	v_mov_b32_e32 v42, v0
	v_mov_b32_e32 v43, v0
	v_mov_b32_e32 v44, v0
	v_mov_b32_e32 v45, v0
	v_mov_b32_e32 v46, v0
	v_mov_b32_e32 v47, v0
	v_mov_b32_e32 v48, v0
	v_mov_b32_e32 v49, v0
	v_mov_b32_e32 v50, v0
	v_mov_b32_e32 v51, v0
	v_mov_b32_e32 v52, v0
	v_mov_b32_e32 v53, v0
	v_mov_b32_e32 v54, v0
	v_mov_b32_e32 v55, v0
	v_mov_b32_e32 v56, v0
	v_mov_b32_e32 v57, v0
	v_mov_b32_e32 v58, v0
	v_mov_b32_e32 v59, v0
	v_mov_b32_e32 v60, v0
	v_mov_b32_e32 v61, v0
	v_mov_b32_e32 v62, v0
	v_mov_b32_e32 v63, v0
	s_branch .LBB0_465

; #define LAS __attribute__((address_space(3)))
; __device__ __forceinline__ unsigned pk2(float lo, float hi) { f32x2_t v = {lo, hi}; bf16x2_t b = __builtin_convertvector(v, bf16x2_t); return __builtin_bit_cast(unsigned, b); }
; __device__ __forceinline__ float fast_exp2(float x) { return __builtin_amdgcn_exp2f(x); }
; __device__ __forceinline__ void hm_stage(LAS unsigned char* wl, const unsigned (&rq)[16], const unsigned (&rz)[16], const unsigned (&rv)[16], float oml, int lane) {
;     float kt[16]; float run = 1.0f;
;     unsigned vpk[8];
; #pragma unroll
;     for (int i = 0; i < 16; ++i) {
;         const float z = bf2f(rz[i]), q = bf2f(rq[i]);
;         const float sg = __builtin_amdgcn_rcpf(1.0f + fast_exp2(z * LOG2E));
;         const float k = oml * sg;
;         run = fmaxf(run * (1.0f - k), 8.673617379884035e-19f);
;         const float ieb = __builtin_amdgcn_rcpf(run);
;         kt[i] = k * ieb;
;         *(LAS unsigned short*)(wl + HM_QT + i * HM_QP + lane * 2) = (unsigned short)pk2(q * run, 0.f);
;         *(LAS unsigned short*)(wl + HM_KT + i * HM_QP + lane * 2) = (unsigned short)pk2(kt[i], 0.f);
;         if (i & 1) vpk[i >> 1] = rv[i - 1] | (rv[i] << 16);
;     }
;     const float eB = run;
;     *(LAS float*)(wl + HM_EB + lane * 4) = eB;
.LBB0_465:
	s_waitcnt vmcnt(48)
	v_mul_f32_e32 v64, 0x3fb8aa3b, v151
	v_exp_f32_e32 v64, v64
	s_nop 0
	v_add_f32_e32 v64, 1.0, v64
	v_rcp_f32_e32 v74, v64
	v_mul_f32_e32 v64, 0x3fb8aa3b, v150
	v_exp_f32_e32 v64, v64
	s_nop 0
	v_add_f32_e32 v64, 1.0, v64
	v_rcp_f32_e32 v75, v64
	v_mul_f32_e32 v64, 0x3fb8aa3b, v158
	v_exp_f32_e32 v64, v64
	v_pk_mul_f32 v[74:75], v[136:137], v[74:75]
	v_sub_f32_e32 v88, 1.0, v74
	v_max_f32_e32 v119, 0x21800000, v88
	v_add_f32_e32 v64, 1.0, v64
	v_mul_f32_e32 v89, v119, v149
	v_rcp_f32_e32 v78, v64
	v_cvt_pk_bf16_f32 v89, v89, s0
	v_mul_f32_e32 v64, 0x3fb8aa3b, v157
	ds_write_b16 v139, v89
	v_sub_f32_e32 v89, 1.0, v75
	v_exp_f32_e32 v64, v64
	v_mul_f32_e32 v89, v89, v119
	v_rcp_f32_e32 v88, v119
	v_max_f32_e32 v119, 0x21800000, v89
	v_rcp_f32_e32 v89, v119
	v_add_f32_e32 v64, 1.0, v64
	v_rcp_f32_e32 v79, v64
	v_mul_f32_e32 v64, 0x3fb8aa3b, v156
	v_pk_mul_f32 v[74:75], v[74:75], v[88:89]
	v_exp_f32_e32 v64, v64
	v_cvt_pk_bf16_f32 v88, v74, s0
	ds_write_b16 v139, v88 offset:2304
	v_mul_f32_e32 v88, v119, v148
	v_pk_mul_f32 v[78:79], v[136:137], v[78:79]
	v_cvt_pk_bf16_f32 v88, v88, s0
	v_sub_f32_e32 v117, 1.0, v78
	ds_write_b16 v139, v88 offset:144
	v_cvt_pk_bf16_f32 v88, v75, s0
	v_add_f32_e32 v64, 1.0, v64
	ds_write_b16 v139, v88 offset:2448
	v_mul_f32_e32 v88, v117, v119
	v_rcp_f32_e32 v82, v64
	v_max_f32_e32 v89, 0x21800000, v88
	v_mul_f32_e32 v64, 0x3fb8aa3b, v166
	v_sub_f32_e32 v118, 1.0, v79
	v_mul_f32_e32 v90, v89, v147
	v_exp_f32_e32 v64, v64
	v_rcp_f32_e32 v88, v89
	v_cvt_pk_bf16_f32 v90, v90, s0
	v_mul_f32_e32 v89, v118, v89
	ds_write_b16 v139, v90 offset:288
	v_max_f32_e32 v90, 0x21800000, v89
	v_rcp_f32_e32 v89, v90
	v_add_f32_e32 v64, 1.0, v64
	v_rcp_f32_e32 v83, v64
	v_mul_f32_e32 v64, 0x3fb8aa3b, v165
	v_pk_mul_f32 v[78:79], v[78:79], v[88:89]
	v_exp_f32_e32 v64, v64
	v_cvt_pk_bf16_f32 v88, v78, s0
	ds_write_b16 v139, v88 offset:2592
	v_mul_f32_e32 v88, v90, v155
	v_pk_mul_f32 v[82:83], v[136:137], v[82:83]
	v_cvt_pk_bf16_f32 v88, v88, s0
	v_sub_f32_e32 v115, 1.0, v82
	ds_write_b16 v139, v88 offset:432
	v_cvt_pk_bf16_f32 v88, v79, s0
	v_add_f32_e32 v64, 1.0, v64
	ds_write_b16 v139, v88 offset:2736
	v_mul_f32_e32 v88, v115, v90
	v_rcp_f32_e32 v84, v64
	v_max_f32_e32 v89, 0x21800000, v88
	v_mul_f32_e32 v64, 0x3fb8aa3b, v175
	v_sub_f32_e32 v116, 1.0, v83
	v_mul_f32_e32 v90, v89, v154
	v_exp_f32_e32 v64, v64
	v_rcp_f32_e32 v88, v89
	v_cvt_pk_bf16_f32 v90, v90, s0
	v_mul_f32_e32 v89, v116, v89
	ds_write_b16 v139, v90 offset:576
	v_max_f32_e32 v90, 0x21800000, v89
	v_rcp_f32_e32 v89, v90
	v_add_f32_e32 v64, 1.0, v64
	v_rcp_f32_e32 v85, v64
	v_mul_f32_e32 v64, 0x3fb8aa3b, v174
	v_pk_mul_f32 v[82:83], v[82:83], v[88:89]
	v_exp_f32_e32 v64, v64
	v_cvt_pk_bf16_f32 v88, v82, s0
	ds_write_b16 v139, v88 offset:2880
	v_mul_f32_e32 v88, v90, v164
	v_pk_mul_f32 v[84:85], v[136:137], v[84:85]
	v_cvt_pk_bf16_f32 v88, v88, s0
	v_sub_f32_e32 v113, 1.0, v84
	ds_write_b16 v139, v88 offset:720
	v_cvt_pk_bf16_f32 v88, v83, s0
	v_add_f32_e32 v64, 1.0, v64
	ds_write_b16 v139, v88 offset:3024
	v_mul_f32_e32 v88, v113, v90
	v_rcp_f32_e32 v86, v64
	v_max_f32_e32 v89, 0x21800000, v88
	v_mul_f32_e32 v64, 0x3fb8aa3b, v173
	v_sub_f32_e32 v114, 1.0, v85
	v_mul_f32_e32 v90, v89, v163
	v_exp_f32_e32 v64, v64
	v_rcp_f32_e32 v88, v89
	v_cvt_pk_bf16_f32 v90, v90, s0
	v_mul_f32_e32 v89, v114, v89
	ds_write_b16 v139, v90 offset:864
	v_max_f32_e32 v90, 0x21800000, v89
	v_rcp_f32_e32 v89, v90
	v_add_f32_e32 v64, 1.0, v64
	v_rcp_f32_e32 v87, v64
	v_mul_f32_e32 v64, 0x3fb8aa3b, v190
	v_pk_mul_f32 v[84:85], v[84:85], v[88:89]
	v_exp_f32_e32 v64, v64
	v_cvt_pk_bf16_f32 v88, v84, s0
	ds_write_b16 v139, v88 offset:3168
	v_mul_f32_e32 v88, v90, v162
	v_pk_mul_f32 v[86:87], v[136:137], v[86:87]
	v_cvt_pk_bf16_f32 v88, v88, s0
	v_sub_f32_e32 v111, 1.0, v86
	ds_write_b16 v139, v88 offset:1008
	v_cvt_pk_bf16_f32 v88, v85, s0
	v_add_f32_e32 v64, 1.0, v64
	ds_write_b16 v139, v88 offset:3312
	v_mul_f32_e32 v88, v111, v90
	v_rcp_f32_e32 v80, v64
	v_max_f32_e32 v89, 0x21800000, v88
	v_mul_f32_e32 v64, 0x3fb8aa3b, v189
	v_sub_f32_e32 v112, 1.0, v87
	v_mul_f32_e32 v90, v89, v172
	v_exp_f32_e32 v64, v64
	v_rcp_f32_e32 v88, v89
	v_cvt_pk_bf16_f32 v90, v90, s0
	v_mul_f32_e32 v89, v112, v89
	ds_write_b16 v139, v90 offset:1152
	v_max_f32_e32 v90, 0x21800000, v89
	v_rcp_f32_e32 v89, v90
	v_add_f32_e32 v64, 1.0, v64
	v_rcp_f32_e32 v81, v64
	v_mul_f32_e32 v64, 0x3fb8aa3b, v188
	v_pk_mul_f32 v[86:87], v[86:87], v[88:89]
	v_exp_f32_e32 v64, v64
	v_cvt_pk_bf16_f32 v88, v86, s0
	ds_write_b16 v139, v88 offset:3456
	v_mul_f32_e32 v88, v90, v171
	v_pk_mul_f32 v[80:81], v[136:137], v[80:81]
	v_cvt_pk_bf16_f32 v88, v88, s0
	v_sub_f32_e32 v109, 1.0, v80
	ds_write_b16 v139, v88 offset:1296
	v_cvt_pk_bf16_f32 v88, v87, s0
	v_add_f32_e32 v64, 1.0, v64
	ds_write_b16 v139, v88 offset:3600
	v_mul_f32_e32 v88, v109, v90
	v_rcp_f32_e32 v76, v64
	v_max_f32_e32 v89, 0x21800000, v88
	v_mul_f32_e32 v64, 0x3fb8aa3b, v198
	v_sub_f32_e32 v110, 1.0, v81
	v_mul_f32_e32 v90, v89, v170
	v_exp_f32_e32 v64, v64
	v_rcp_f32_e32 v88, v89
	v_cvt_pk_bf16_f32 v90, v90, s0
	v_mul_f32_e32 v89, v110, v89
	ds_write_b16 v139, v90 offset:1440
	v_max_f32_e32 v90, 0x21800000, v89
	v_rcp_f32_e32 v89, v90
	v_add_f32_e32 v64, 1.0, v64
	v_rcp_f32_e32 v77, v64
	v_mul_f32_e32 v64, 0x3fb8aa3b, v197
	v_pk_mul_f32 v[80:81], v[80:81], v[88:89]
	v_exp_f32_e32 v64, v64
	v_cvt_pk_bf16_f32 v88, v80, s0
	ds_write_b16 v139, v88 offset:3744
	v_mul_f32_e32 v88, v90, v187
	v_pk_mul_f32 v[76:77], v[136:137], v[76:77]
	v_cvt_pk_bf16_f32 v88, v88, s0
	v_sub_f32_e32 v107, 1.0, v76
	ds_write_b16 v139, v88 offset:1584
; #define LAS __attribute__((address_space(3)))
; __device__ __forceinline__ unsigned pk2(float lo, float hi) { f32x2_t v = {lo, hi}; bf16x2_t b = __builtin_convertvector(v, bf16x2_t); return __builtin_bit_cast(unsigned, b); }
; #define HM_LOAD(RQ, RZ, RV, j_) do { _Pragma("unroll") for (int i = 0; i < 16; ++i) { const bf16_t* pr_ = proj + HM_TOK((j_) * 16 + i) * INW; RQ[i] = pr_[qc]; RZ[i] = pr_[zc]; RV[i] = pr_[vc]; } } while (0)
; __device__ __forceinline__ void hm_stage(LAS unsigned char* wl, const unsigned (&rq)[16], const unsigned (&rz)[16], const unsigned (&rv)[16], float oml, int lane) {
;     ...
;         *(LAS unsigned short*)(wl + HM_QT + i * HM_QP + lane * 2) = (unsigned short)pk2(q * run, 0.f);
;         *(LAS unsigned short*)(wl + HM_KT + i * HM_QP + lane * 2) = (unsigned short)pk2(kt[i], 0.f);
;         if (i & 1) vpk[i >> 1] = rv[i - 1] | (rv[i] << 16);
;     }
;     const float eB = run;
;     *(LAS float*)(wl + HM_EB + lane * 4) = eB;
;     u32x4 w0, w1;
;     w0.x = pk2(kt[0] * eB, kt[1] * eB); w0.y = pk2(kt[2] * eB, kt[3] * eB); w0.z = pk2(kt[4] * eB, kt[5] * eB); w0.w = pk2(kt[6] * eB, kt[7] * eB);
;     w1.x = pk2(kt[8] * eB, kt[9] * eB); w1.y = pk2(kt[10] * eB, kt[11] * eB); w1.z = pk2(kt[12] * eB, kt[13] * eB); w1.w = pk2(kt[14] * eB, kt[15] * eB);
;     *(LAS u32x4*)(wl + HM_KD + lane * 32) = w0; *(LAS u32x4*)(wl + HM_KD + lane * 32 + 16) = w1;
;     *(LAS u32x4*)(wl + HM_VT + lane * 32) = (u32x4){vpk[0], vpk[1], vpk[2], vpk[3]}; *(LAS u32x4*)(wl + HM_VT + lane * 32 + 16) = (u32x4){vpk[4], vpk[5], vpk[6], vpk[7]};
; __device__ __forceinline__ void hgrn_mfma_unit(const Params& P, int l, LAS unsigned char* lds, int b, int half) {
;     ...
;         for (int j = 0; j < NSC; j += 2) {
;             hm_stage(wl, aq, az, av, oml, lane);
;             if (j + 2 < NSC) HM_LOAD(aq, az, av, j + 2);
	v_cvt_pk_bf16_f32 v88, v81, s0
	v_add_f32_e32 v64, 1.0, v64
	ds_write_b16 v139, v88 offset:3888
	v_mul_f32_e32 v88, v107, v90
	v_rcp_f32_e32 v72, v64
	v_max_f32_e32 v89, 0x21800000, v88
	v_mul_f32_e32 v64, 0x3fb8aa3b, v211
	v_sub_f32_e32 v108, 1.0, v77
	v_mul_f32_e32 v90, v89, v186
	v_exp_f32_e32 v64, v64
	v_rcp_f32_e32 v88, v89
	v_cvt_pk_bf16_f32 v90, v90, s0
	v_mul_f32_e32 v89, v108, v89
	ds_write_b16 v139, v90 offset:1728
	v_max_f32_e32 v90, 0x21800000, v89
	v_rcp_f32_e32 v89, v90
	v_add_f32_e32 v64, 1.0, v64
	v_rcp_f32_e32 v73, v64
	v_pk_mul_f32 v[88:89], v[76:77], v[88:89]
	v_cvt_pk_bf16_f32 v76, v88, s0
	ds_write_b16 v139, v76 offset:4032
	v_mul_f32_e32 v76, v90, v196
	v_pk_mul_f32 v[72:73], v[136:137], v[72:73]
	v_cvt_pk_bf16_f32 v76, v76, s0
	v_sub_f32_e32 v105, 1.0, v72
	ds_write_b16 v139, v76 offset:1872
	v_cvt_pk_bf16_f32 v76, v89, s0
	ds_write_b16 v139, v76 offset:4176
	v_mul_f32_e32 v76, v105, v90
	v_max_f32_e32 v77, 0x21800000, v76
	v_sub_f32_e32 v106, 1.0, v73
	v_mul_f32_e32 v90, v77, v195
	v_rcp_f32_e32 v76, v77
	v_cvt_pk_bf16_f32 v90, v90, s0
	v_mul_f32_e32 v77, v106, v77
	ds_write_b16 v139, v90 offset:2016
	v_max_f32_e32 v90, 0x21800000, v77
	v_rcp_f32_e32 v77, v90
	s_add_i32 s28, s9, 2
	s_cmpk_gt_u32 s9, 0x8d
	v_pk_mul_f32 v[92:93], v[72:73], v[76:77]
	v_pk_mul_f32 v[76:77], v[84:85], v[90:91] op_sel_hi:[1,0]
	v_cvt_pk_bf16_f32 v72, v92, s0
	ds_write_b16 v139, v72 offset:4320
	v_mul_f32_e32 v72, v90, v194
	v_cvt_pk_bf16_f32 v72, v72, s0
	ds_write_b16 v139, v72 offset:2160
	v_cvt_pk_bf16_f32 v72, v93, s0
	ds_write_b16 v139, v72 offset:4464
	v_pk_mul_f32 v[72:73], v[74:75], v[90:91] op_sel_hi:[1,0]
	v_pk_mul_f32 v[74:75], v[78:79], v[90:91] op_sel_hi:[1,0]
	v_cvt_pk_bf16_f32 v72, v72, v73
	v_cvt_pk_bf16_f32 v73, v74, v75
	v_pk_mul_f32 v[74:75], v[82:83], v[90:91] op_sel_hi:[1,0]
	v_pk_mul_f32 v[78:79], v[80:81], v[90:91] op_sel_hi:[1,0]
	v_cvt_pk_bf16_f32 v74, v74, v75
	v_cvt_pk_bf16_f32 v75, v76, v77
	v_pk_mul_f32 v[76:77], v[86:87], v[90:91] op_sel_hi:[1,0]
	s_cselect_b64 s[50:51], -1, 0
	v_add_u32_e32 v207, v133, v132
	v_cvt_pk_bf16_f32 v76, v76, v77
	v_cvt_pk_bf16_f32 v77, v78, v79
	v_pk_mul_f32 v[78:79], v[88:89], v[90:91] op_sel_hi:[1,0]
	v_pk_mul_f32 v[80:81], v[92:93], v[90:91] op_sel_hi:[1,0]
	s_and_b64 vcc, exec, s[50:51]
	v_lshl_or_b32 v64, v152, 16, v153
	v_lshl_or_b32 v65, v160, 16, v161
	v_lshl_or_b32 v66, v169, 16, v159
	v_lshl_or_b32 v67, v167, 16, v168
	v_lshl_or_b32 v68, v176, 16, v177
	v_lshl_or_b32 v69, v192, 16, v193
	v_lshl_or_b32 v70, v210, 16, v191
	v_lshl_or_b32 v71, v199, 16, v209
	ds_write_b32 v207, v90 offset:8704
	v_cvt_pk_bf16_f32 v78, v78, v79
	v_cvt_pk_bf16_f32 v79, v80, v81
	ds_write_b128 v146, v[72:75] offset:4608
	ds_write_b128 v146, v[76:79] offset:4624
	ds_write_b128 v146, v[64:67] offset:6656
	ds_write_b128 v146, v[68:71] offset:6672
	s_cbranch_vccnz .Lhm_a_skip
	s_lshl_b32 s12, s28, 4
	s_mov_b32 s18, 0x1600
	s_mov_b32 s19, 0
	s_cmp_eq_u64 s[38:39], 0
	s_cbranch_scc1 .Lhm_a_go
	s_cmp_lt_u32 s28, 16
	s_movk_i32 s13, 0x9ff
	s_cselect_b32 s13, 0xff, s13
	s_sub_u32 s12, s13, s12
	s_mov_b32 s18, 0xffffea00
	s_mov_b32 s19, -1
.Lhm_a_go:
	s_add_u32 s12, s12, s64
	s_mul_i32 s12, s12, 0x1600
	s_add_u32 s12, s56, s12
	s_addc_u32 s13, s57, 0
	v_lshlrev_b32_e32 v64, 1, v130
	v_lshlrev_b32_e32 v65, 1, v134
	global_load_short_d16_hi v149, v64, s[12:13] offset:1536
	global_load_short_d16_hi v151, v65, s[12:13]
	global_load_ushort v153, v64, s[12:13] offset:3072
	s_add_u32 s12, s12, s18
	s_addc_u32 s13, s13, s19
	global_load_short_d16_hi v148, v64, s[12:13] offset:1536
	global_load_short_d16_hi v150, v65, s[12:13]
	global_load_ushort v152, v64, s[12:13] offset:3072
	s_add_u32 s12, s12, s18
	s_addc_u32 s13, s13, s19
	global_load_short_d16_hi v147, v64, s[12:13] offset:1536
	global_load_short_d16_hi v158, v65, s[12:13]
	global_load_ushort v161, v64, s[12:13] offset:3072
	s_add_u32 s12, s12, s18
	s_addc_u32 s13, s13, s19
	global_load_short_d16_hi v155, v64, s[12:13] offset:1536
	global_load_short_d16_hi v157, v65, s[12:13]
	global_load_ushort v160, v64, s[12:13] offset:3072
	s_add_u32 s12, s12, s18
	s_addc_u32 s13, s13, s19
	global_load_short_d16_hi v154, v64, s[12:13] offset:1536
	global_load_short_d16_hi v156, v65, s[12:13]
	global_load_ushort v159, v64, s[12:13] offset:3072
	s_add_u32 s12, s12, s18
	s_addc_u32 s13, s13, s19
	global_load_short_d16_hi v164, v64, s[12:13] offset:1536
	global_load_short_d16_hi v166, v65, s[12:13]
	global_load_ushort v169, v64, s[12:13] offset:3072
	s_add_u32 s12, s12, s18
	s_addc_u32 s13, s13, s19
	global_load_short_d16_hi v163, v64, s[12:13] offset:1536
	global_load_short_d16_hi v165, v65, s[12:13]
	global_load_ushort v168, v64, s[12:13] offset:3072
	s_add_u32 s12, s12, s18
	s_addc_u32 s13, s13, s19
	global_load_short_d16_hi v162, v64, s[12:13] offset:1536
	global_load_short_d16_hi v175, v65, s[12:13]
	global_load_ushort v167, v64, s[12:13] offset:3072
	s_add_u32 s12, s12, s18
	s_addc_u32 s13, s13, s19
	global_load_short_d16_hi v172, v64, s[12:13] offset:1536
	global_load_short_d16_hi v174, v65, s[12:13]
	global_load_ushort v177, v64, s[12:13] offset:3072
	s_add_u32 s12, s12, s18
	s_addc_u32 s13, s13, s19
	global_load_short_d16_hi v171, v64, s[12:13] offset:1536
	global_load_short_d16_hi v173, v65, s[12:13]
	global_load_ushort v176, v64, s[12:13] offset:3072
	s_add_u32 s12, s12, s18
	s_addc_u32 s13, s13, s19
	global_load_short_d16_hi v170, v64, s[12:13] offset:1536
	global_load_short_d16_hi v190, v65, s[12:13]
	global_load_ushort v193, v64, s[12:13] offset:3072
	s_add_u32 s12, s12, s18
	s_addc_u32 s13, s13, s19
	global_load_short_d16_hi v187, v64, s[12:13] offset:1536
	global_load_short_d16_hi v189, v65, s[12:13]
	global_load_ushort v192, v64, s[12:13] offset:3072
	s_add_u32 s12, s12, s18
	s_addc_u32 s13, s13, s19
	global_load_short_d16_hi v186, v64, s[12:13] offset:1536
	global_load_short_d16_hi v188, v65, s[12:13]
	global_load_ushort v191, v64, s[12:13] offset:3072
	s_add_u32 s12, s12, s18
	s_addc_u32 s13, s13, s19
	global_load_short_d16_hi v196, v64, s[12:13] offset:1536
	global_load_short_d16_hi v198, v65, s[12:13]
	global_load_ushort v210, v64, s[12:13] offset:3072
	s_add_u32 s12, s12, s18
	s_addc_u32 s13, s13, s19
	global_load_short_d16_hi v195, v64, s[12:13] offset:1536
	global_load_short_d16_hi v197, v65, s[12:13]
	global_load_ushort v209, v64, s[12:13] offset:3072
	s_add_u32 s12, s12, s18
	s_addc_u32 s13, s13, s19
	global_load_short_d16_hi v194, v64, s[12:13] offset:1536
	global_load_short_d16_hi v211, v65, s[12:13]
	global_load_ushort v199, v64, s[12:13] offset:3072
	s_branch .LBB0_563

; #define LAS __attribute__((address_space(3)))
; __device__ __forceinline__ unsigned pk2(float lo, float hi) { f32x2_t v = {lo, hi}; bf16x2_t b = __builtin_convertvector(v, bf16x2_t); return __builtin_bit_cast(unsigned, b); }
; __device__ __forceinline__ float fast_exp2(float x) { return __builtin_amdgcn_exp2f(x); }
; __device__ __forceinline__ void hm_stage(LAS unsigned char* wl, const unsigned (&rq)[16], const unsigned (&rz)[16], const unsigned (&rv)[16], float oml, int lane) {
;     float kt[16]; float run = 1.0f;
;     unsigned vpk[8];
; #pragma unroll
;     for (int i = 0; i < 16; ++i) {
;         const float z = bf2f(rz[i]), q = bf2f(rq[i]);
;         const float sg = __builtin_amdgcn_rcpf(1.0f + fast_exp2(z * LOG2E));
;         const float k = oml * sg;
;         run = fmaxf(run * (1.0f - k), 8.673617379884035e-19f);
;         const float ieb = __builtin_amdgcn_rcpf(run);
;         kt[i] = k * ieb;
;         *(LAS unsigned short*)(wl + HM_QT + i * HM_QP + lane * 2) = (unsigned short)pk2(q * run, 0.f);
;         *(LAS unsigned short*)(wl + HM_KT + i * HM_QP + lane * 2) = (unsigned short)pk2(kt[i], 0.f);
;         if (i & 1) vpk[i >> 1] = rv[i - 1] | (rv[i] << 16);
;     }
;     const float eB = run;
;     *(LAS float*)(wl + HM_EB + lane * 4) = eB;
.LBB0_584:
	s_or_b64 exec, exec, s[52:53]
	v_ashrrev_i32_e32 v5, 31, v4
	v_lshl_add_u64 v[4:5], v[4:5], 0, s[64:65]
	v_lshlrev_b64 v[4:5], 10, v[4:5]
	v_lshl_add_u64 v[4:5], v[140:141], 0, v[4:5]
	global_store_dwordx4 v[4:5], v[68:71], off
	global_store_dwordx4 v[4:5], v[72:75], off offset:64
	global_store_dwordx4 v[4:5], v[76:79], off offset:128
	global_store_dwordx4 v[4:5], v[80:83], off offset:192
	s_waitcnt vmcnt(52)
	v_mul_f32_e32 v4, 0x3fb8aa3b, v216
	v_exp_f32_e32 v4, v4
	s_nop 0
	v_add_f32_e32 v4, 1.0, v4
	v_rcp_f32_e32 v10, v4
	v_mul_f32_e32 v4, 0x3fb8aa3b, v215
	v_exp_f32_e32 v4, v4
	s_nop 0
	v_add_f32_e32 v4, 1.0, v4
	v_rcp_f32_e32 v11, v4
	v_mul_f32_e32 v4, 0x3fb8aa3b, v224
	v_exp_f32_e32 v4, v4
	v_pk_mul_f32 v[10:11], v[136:137], v[10:11]
	v_sub_f32_e32 v88, 1.0, v10
	v_max_f32_e32 v119, 0x21800000, v88
	v_add_f32_e32 v4, 1.0, v4
	v_mul_f32_e32 v89, v119, v214
	v_rcp_f32_e32 v78, v4
	v_cvt_pk_bf16_f32 v89, v89, s0
	v_mul_f32_e32 v4, 0x3fb8aa3b, v222
	ds_write_b16 v139, v89
	v_sub_f32_e32 v89, 1.0, v11
	v_exp_f32_e32 v4, v4
	v_mul_f32_e32 v89, v89, v119
	v_rcp_f32_e32 v88, v119
	v_max_f32_e32 v119, 0x21800000, v89
	v_rcp_f32_e32 v89, v119
	v_add_f32_e32 v4, 1.0, v4
	v_rcp_f32_e32 v79, v4
	v_mul_f32_e32 v4, 0x3fb8aa3b, v221
	v_pk_mul_f32 v[10:11], v[10:11], v[88:89]
	v_exp_f32_e32 v4, v4
	v_cvt_pk_bf16_f32 v88, v10, s0
	ds_write_b16 v139, v88 offset:2304
	v_mul_f32_e32 v88, v119, v213
	v_pk_mul_f32 v[78:79], v[136:137], v[78:79]
	v_cvt_pk_bf16_f32 v88, v88, s0
	v_sub_f32_e32 v117, 1.0, v78
	ds_write_b16 v139, v88 offset:144
	v_cvt_pk_bf16_f32 v88, v11, s0
	v_add_f32_e32 v4, 1.0, v4
	ds_write_b16 v139, v88 offset:2448
	v_mul_f32_e32 v88, v117, v119
	v_rcp_f32_e32 v82, v4
	v_max_f32_e32 v89, 0x21800000, v88
	v_mul_f32_e32 v4, 0x3fb8aa3b, v231
	v_sub_f32_e32 v118, 1.0, v79
	v_mul_f32_e32 v90, v89, v212
	v_exp_f32_e32 v4, v4
	v_rcp_f32_e32 v88, v89
	v_cvt_pk_bf16_f32 v90, v90, s0
	v_mul_f32_e32 v89, v118, v89
	ds_write_b16 v139, v90 offset:288
	v_max_f32_e32 v90, 0x21800000, v89
	v_rcp_f32_e32 v89, v90
	v_add_f32_e32 v4, 1.0, v4
	v_rcp_f32_e32 v83, v4
	v_mul_f32_e32 v4, 0x3fb8aa3b, v230
	v_pk_mul_f32 v[78:79], v[78:79], v[88:89]
	v_exp_f32_e32 v4, v4
	v_cvt_pk_bf16_f32 v88, v78, s0
	ds_write_b16 v139, v88 offset:2592
	v_mul_f32_e32 v88, v90, v220
	v_pk_mul_f32 v[82:83], v[136:137], v[82:83]
	v_cvt_pk_bf16_f32 v88, v88, s0
	v_sub_f32_e32 v115, 1.0, v82
	ds_write_b16 v139, v88 offset:432
	v_cvt_pk_bf16_f32 v88, v79, s0
	v_add_f32_e32 v4, 1.0, v4
	ds_write_b16 v139, v88 offset:2736
	v_mul_f32_e32 v88, v115, v90
	v_rcp_f32_e32 v84, v4
	v_max_f32_e32 v89, 0x21800000, v88
	v_mul_f32_e32 v4, 0x3fb8aa3b, v240
	v_sub_f32_e32 v116, 1.0, v83
	v_mul_f32_e32 v90, v89, v219
	v_exp_f32_e32 v4, v4
	v_rcp_f32_e32 v88, v89
	v_cvt_pk_bf16_f32 v90, v90, s0
	v_mul_f32_e32 v89, v116, v89
	ds_write_b16 v139, v90 offset:576
	v_max_f32_e32 v90, 0x21800000, v89
	v_rcp_f32_e32 v89, v90
	v_add_f32_e32 v4, 1.0, v4
	v_rcp_f32_e32 v85, v4
	v_mul_f32_e32 v4, 0x3fb8aa3b, v239
	v_pk_mul_f32 v[82:83], v[82:83], v[88:89]
	v_exp_f32_e32 v4, v4
	v_cvt_pk_bf16_f32 v88, v82, s0
	ds_write_b16 v139, v88 offset:2880
	v_mul_f32_e32 v88, v90, v229
	v_pk_mul_f32 v[84:85], v[136:137], v[84:85]
	v_cvt_pk_bf16_f32 v88, v88, s0
	v_sub_f32_e32 v113, 1.0, v84
	ds_write_b16 v139, v88 offset:720
	v_cvt_pk_bf16_f32 v88, v83, s0
	v_add_f32_e32 v4, 1.0, v4
	ds_write_b16 v139, v88 offset:3024
	v_mul_f32_e32 v88, v113, v90
	v_rcp_f32_e32 v86, v4
	v_max_f32_e32 v89, 0x21800000, v88
	v_mul_f32_e32 v4, 0x3fb8aa3b, v238
	v_sub_f32_e32 v114, 1.0, v85
	v_mul_f32_e32 v90, v89, v228
	v_exp_f32_e32 v4, v4
	v_rcp_f32_e32 v88, v89
	v_cvt_pk_bf16_f32 v90, v90, s0
	v_mul_f32_e32 v89, v114, v89
	ds_write_b16 v139, v90 offset:864
	v_max_f32_e32 v90, 0x21800000, v89
	v_rcp_f32_e32 v89, v90
	v_add_f32_e32 v4, 1.0, v4
	v_rcp_f32_e32 v87, v4
	v_mul_f32_e32 v4, 0x3fb8aa3b, v248
	v_pk_mul_f32 v[84:85], v[84:85], v[88:89]
	v_exp_f32_e32 v4, v4
	v_cvt_pk_bf16_f32 v88, v84, s0
	ds_write_b16 v139, v88 offset:3168
	v_mul_f32_e32 v88, v90, v227
	v_pk_mul_f32 v[86:87], v[136:137], v[86:87]
	v_cvt_pk_bf16_f32 v88, v88, s0
	v_sub_f32_e32 v111, 1.0, v86
	ds_write_b16 v139, v88 offset:1008
	v_cvt_pk_bf16_f32 v88, v85, s0
	v_add_f32_e32 v4, 1.0, v4
	ds_write_b16 v139, v88 offset:3312
	v_mul_f32_e32 v88, v111, v90
	v_rcp_f32_e32 v80, v4
	v_max_f32_e32 v89, 0x21800000, v88
	v_mul_f32_e32 v4, 0x3fb8aa3b, v246
	v_sub_f32_e32 v112, 1.0, v87
	v_mul_f32_e32 v90, v89, v237
	v_exp_f32_e32 v4, v4
	v_rcp_f32_e32 v88, v89
	v_cvt_pk_bf16_f32 v90, v90, s0
	v_mul_f32_e32 v89, v112, v89
	ds_write_b16 v139, v90 offset:1152
	v_max_f32_e32 v90, 0x21800000, v89
	v_rcp_f32_e32 v89, v90
	v_add_f32_e32 v4, 1.0, v4
	v_rcp_f32_e32 v81, v4
	v_mul_f32_e32 v4, 0x3fb8aa3b, v245
	v_pk_mul_f32 v[86:87], v[86:87], v[88:89]
	v_exp_f32_e32 v4, v4
	v_cvt_pk_bf16_f32 v88, v86, s0
	ds_write_b16 v139, v88 offset:3456
	v_mul_f32_e32 v88, v90, v236
	v_pk_mul_f32 v[80:81], v[136:137], v[80:81]
	v_cvt_pk_bf16_f32 v88, v88, s0
	v_sub_f32_e32 v109, 1.0, v80
	ds_write_b16 v139, v88 offset:1296
	v_cvt_pk_bf16_f32 v88, v87, s0
	v_add_f32_e32 v4, 1.0, v4
	ds_write_b16 v139, v88 offset:3600
	v_mul_f32_e32 v88, v109, v90
	v_rcp_f32_e32 v76, v4
	v_max_f32_e32 v89, 0x21800000, v88
	v_mul_f32_e32 v4, 0x3fb8aa3b, v206
	v_sub_f32_e32 v110, 1.0, v81
	v_mul_f32_e32 v90, v89, v235
	v_exp_f32_e32 v4, v4
	v_rcp_f32_e32 v88, v89
	v_cvt_pk_bf16_f32 v90, v90, s0
	v_mul_f32_e32 v89, v110, v89
	ds_write_b16 v139, v90 offset:1440
	v_max_f32_e32 v90, 0x21800000, v89
	v_rcp_f32_e32 v89, v90
	v_add_f32_e32 v4, 1.0, v4
	v_rcp_f32_e32 v77, v4
	v_pk_mul_f32 v[88:89], v[80:81], v[88:89]
; #define LAS __attribute__((address_space(3)))
; __device__ __forceinline__ unsigned pk2(float lo, float hi) { f32x2_t v = {lo, hi}; bf16x2_t b = __builtin_convertvector(v, bf16x2_t); return __builtin_bit_cast(unsigned, b); }
; #define HM_LOAD(RQ, RZ, RV, j_) do { _Pragma("unroll") for (int i = 0; i < 16; ++i) { const bf16_t* pr_ = proj + HM_TOK((j_) * 16 + i) * INW; RQ[i] = pr_[qc]; RZ[i] = pr_[zc]; RV[i] = pr_[vc]; } } while (0)
; __device__ __forceinline__ void hm_stage(LAS unsigned char* wl, const unsigned (&rq)[16], const unsigned (&rz)[16], const unsigned (&rv)[16], float oml, int lane) {
;     ...
;         *(LAS unsigned short*)(wl + HM_QT + i * HM_QP + lane * 2) = (unsigned short)pk2(q * run, 0.f);
;         *(LAS unsigned short*)(wl + HM_KT + i * HM_QP + lane * 2) = (unsigned short)pk2(kt[i], 0.f);
;         if (i & 1) vpk[i >> 1] = rv[i - 1] | (rv[i] << 16);
;     }
;     const float eB = run;
;     *(LAS float*)(wl + HM_EB + lane * 4) = eB;
;     u32x4 w0, w1;
;     w0.x = pk2(kt[0] * eB, kt[1] * eB); w0.y = pk2(kt[2] * eB, kt[3] * eB); w0.z = pk2(kt[4] * eB, kt[5] * eB); w0.w = pk2(kt[6] * eB, kt[7] * eB);
;     w1.x = pk2(kt[8] * eB, kt[9] * eB); w1.y = pk2(kt[10] * eB, kt[11] * eB); w1.z = pk2(kt[12] * eB, kt[13] * eB); w1.w = pk2(kt[14] * eB, kt[15] * eB);
;     *(LAS u32x4*)(wl + HM_KD + lane * 32) = w0; *(LAS u32x4*)(wl + HM_KD + lane * 32 + 16) = w1;
;     *(LAS u32x4*)(wl + HM_VT + lane * 32) = (u32x4){vpk[0], vpk[1], vpk[2], vpk[3]}; *(LAS u32x4*)(wl + HM_VT + lane * 32 + 16) = (u32x4){vpk[4], vpk[5], vpk[6], vpk[7]};
; __device__ __forceinline__ void hgrn_mfma_unit(const Params& P, int l, LAS unsigned char* lds, int b, int half) {
;     ...
;             hm_stage(wl, bq, bz, bv, oml, lane);
;             if (j + 3 < NSC) HM_LOAD(bq, bz, bv, j + 3);
	v_cvt_pk_bf16_f32 v80, v88, s0
	ds_write_b16 v139, v80 offset:3744
	v_mul_f32_e32 v80, v90, v244
	v_pk_mul_f32 v[76:77], v[136:137], v[76:77]
	v_cvt_pk_bf16_f32 v80, v80, s0
	v_sub_f32_e32 v107, 1.0, v76
	ds_write_b16 v139, v80 offset:1584
	v_cvt_pk_bf16_f32 v80, v89, s0
	ds_write_b16 v139, v80 offset:3888
	v_mul_f32_e32 v80, v107, v90
	v_mul_f32_e32 v4, 0x3fb8aa3b, v204
	v_mul_f32_e32 v5, 0x3fb8aa3b, v178
	v_sub_f32_e32 v108, 1.0, v77
	v_max_f32_e32 v81, 0x21800000, v80
	v_exp_f32_e32 v4, v4
	v_exp_f32_e32 v5, v5
	v_rcp_f32_e32 v80, v81
	v_mul_f32_e32 v90, v81, v243
	v_mul_f32_e32 v81, v108, v81
	v_max_f32_e32 v92, 0x21800000, v81
	v_rcp_f32_e32 v81, v92
	v_add_f32_e32 v4, 1.0, v4
	v_add_f32_e32 v5, 1.0, v5
	v_rcp_f32_e32 v4, v4
	v_rcp_f32_e32 v5, v5
	v_cvt_pk_bf16_f32 v90, v90, s0
	ds_write_b16 v139, v90 offset:1728
	v_pk_mul_f32 v[90:91], v[76:77], v[80:81]
	v_cvt_pk_bf16_f32 v76, v90, s0
	ds_write_b16 v139, v76 offset:4032
	v_mul_f32_e32 v76, v92, v205
	v_pk_mul_f32 v[4:5], v[136:137], v[4:5]
	v_cvt_pk_bf16_f32 v76, v76, s0
	v_sub_f32_e32 v105, 1.0, v4
	ds_write_b16 v139, v76 offset:1872
	v_cvt_pk_bf16_f32 v76, v91, s0
	ds_write_b16 v139, v76 offset:4176
	v_mul_f32_e32 v76, v105, v92
	v_sub_f32_e32 v106, 1.0, v5
	v_max_f32_e32 v77, 0x21800000, v76
	v_rcp_f32_e32 v76, v77
	v_mul_f32_e32 v80, v77, v252
	v_mul_f32_e32 v77, v106, v77
	v_max_f32_e32 v92, 0x21800000, v77
	v_rcp_f32_e32 v77, v92
	v_cvt_pk_bf16_f32 v80, v80, s0
	v_pk_mul_f32 v[10:11], v[10:11], v[92:93] op_sel_hi:[1,0]
	v_pk_mul_f32 v[4:5], v[4:5], v[76:77]
	ds_write_b16 v139, v80 offset:2016
	v_cvt_pk_bf16_f32 v76, v4, s0
	ds_write_b16 v139, v76 offset:4320
	v_mul_f32_e32 v76, v92, v251
	v_cvt_pk_bf16_f32 v76, v76, s0
	ds_write_b16 v139, v76 offset:2160
	v_cvt_pk_bf16_f32 v76, v5, s0
	ds_write_b16 v139, v76 offset:4464
	ds_write_b32 v207, v92 offset:8704
	v_cvt_pk_bf16_f32 v76, v10, v11
	v_pk_mul_f32 v[10:11], v[78:79], v[92:93] op_sel_hi:[1,0]
	v_pk_mul_f32 v[4:5], v[4:5], v[92:93] op_sel_hi:[1,0]
	v_cvt_pk_bf16_f32 v77, v10, v11
	v_pk_mul_f32 v[10:11], v[82:83], v[92:93] op_sel_hi:[1,0]
	s_cmpk_gt_u32 s9, 0x8c
	v_cvt_pk_bf16_f32 v78, v10, v11
	v_pk_mul_f32 v[10:11], v[84:85], v[92:93] op_sel_hi:[1,0]
	v_lshl_or_b32 v68, v217, 16, v218
	v_cvt_pk_bf16_f32 v79, v10, v11
	v_pk_mul_f32 v[10:11], v[86:87], v[92:93] op_sel_hi:[1,0]
	v_lshl_or_b32 v69, v225, 16, v226
	v_cvt_pk_bf16_f32 v80, v10, v11
	v_pk_mul_f32 v[10:11], v[88:89], v[92:93] op_sel_hi:[1,0]
	v_lshl_or_b32 v70, v234, 16, v223
	v_cvt_pk_bf16_f32 v81, v10, v11
	v_pk_mul_f32 v[10:11], v[90:91], v[92:93] op_sel_hi:[1,0]
	v_lshl_or_b32 v71, v232, 16, v233
	v_lshl_or_b32 v72, v241, 16, v242
	v_lshl_or_b32 v73, v249, 16, v250
	v_lshl_or_b32 v74, v180, 16, v247
	v_lshl_or_b32 v75, v208, 16, v179
	v_cvt_pk_bf16_f32 v82, v10, v11
	v_cvt_pk_bf16_f32 v83, v4, v5
	ds_write_b128 v146, v[76:79] offset:4608
	ds_write_b128 v146, v[80:83] offset:4624
	ds_write_b128 v146, v[68:71] offset:6656
	ds_write_b128 v146, v[72:75] offset:6672
	s_cbranch_scc1 .LBB0_697
	s_add_u32 s12, s15, 48
	s_mov_b32 s18, 0x1600
	s_mov_b32 s19, 0
	s_cmp_eq_u64 s[38:39], 0
	s_cbranch_scc1 .Lhm_b_go
	s_cmp_lt_u32 s9, 13
	s_movk_i32 s13, 0x9ff
	s_cselect_b32 s13, 0xff, s13
	s_sub_u32 s12, s13, s12
	s_mov_b32 s18, 0xffffea00
	s_mov_b32 s19, -1
.Lhm_b_go:
	s_add_u32 s12, s12, s64
	s_mul_i32 s12, s12, 0x1600
	s_add_u32 s12, s56, s12
	s_addc_u32 s13, s57, 0
	v_lshlrev_b32_e32 v68, 1, v130
	v_lshlrev_b32_e32 v69, 1, v134
	global_load_short_d16_hi v214, v68, s[12:13] offset:1536
	global_load_short_d16_hi v216, v69, s[12:13]
	global_load_ushort v218, v68, s[12:13] offset:3072
	s_add_u32 s12, s12, s18
	s_addc_u32 s13, s13, s19
	global_load_short_d16_hi v213, v68, s[12:13] offset:1536
	global_load_short_d16_hi v215, v69, s[12:13]
	global_load_ushort v217, v68, s[12:13] offset:3072
	s_add_u32 s12, s12, s18
	s_addc_u32 s13, s13, s19
	global_load_short_d16_hi v212, v68, s[12:13] offset:1536
	global_load_short_d16_hi v224, v69, s[12:13]
	global_load_ushort v226, v68, s[12:13] offset:3072
	s_add_u32 s12, s12, s18
	s_addc_u32 s13, s13, s19
	global_load_short_d16_hi v220, v68, s[12:13] offset:1536
	global_load_short_d16_hi v222, v69, s[12:13]
	global_load_ushort v225, v68, s[12:13] offset:3072
	s_add_u32 s12, s12, s18
	s_addc_u32 s13, s13, s19
	global_load_short_d16_hi v219, v68, s[12:13] offset:1536
	global_load_short_d16_hi v221, v69, s[12:13]
	global_load_ushort v223, v68, s[12:13] offset:3072
	s_add_u32 s12, s12, s18
	s_addc_u32 s13, s13, s19
	global_load_short_d16_hi v229, v68, s[12:13] offset:1536
	global_load_short_d16_hi v231, v69, s[12:13]
	global_load_ushort v234, v68, s[12:13] offset:3072
	s_add_u32 s12, s12, s18
	s_addc_u32 s13, s13, s19
	global_load_short_d16_hi v228, v68, s[12:13] offset:1536
	global_load_short_d16_hi v230, v69, s[12:13]
	global_load_ushort v233, v68, s[12:13] offset:3072
	s_add_u32 s12, s12, s18
	s_addc_u32 s13, s13, s19
	global_load_short_d16_hi v227, v68, s[12:13] offset:1536
	global_load_short_d16_hi v240, v69, s[12:13]
	global_load_ushort v232, v68, s[12:13] offset:3072
	s_add_u32 s12, s12, s18
	s_addc_u32 s13, s13, s19
	global_load_short_d16_hi v237, v68, s[12:13] offset:1536
	global_load_short_d16_hi v239, v69, s[12:13]
	global_load_ushort v242, v68, s[12:13] offset:3072
	s_add_u32 s12, s12, s18
	s_addc_u32 s13, s13, s19
	global_load_short_d16_hi v236, v68, s[12:13] offset:1536
	global_load_short_d16_hi v238, v69, s[12:13]
	global_load_ushort v241, v68, s[12:13] offset:3072
	s_add_u32 s12, s12, s18
	s_addc_u32 s13, s13, s19
	global_load_short_d16_hi v235, v68, s[12:13] offset:1536
	global_load_short_d16_hi v248, v69, s[12:13]
	global_load_ushort v250, v68, s[12:13] offset:3072
	s_add_u32 s12, s12, s18
	s_addc_u32 s13, s13, s19
	global_load_short_d16_hi v244, v68, s[12:13] offset:1536
	global_load_short_d16_hi v246, v69, s[12:13]
	global_load_ushort v249, v68, s[12:13] offset:3072
	s_add_u32 s12, s12, s18
	s_addc_u32 s13, s13, s19
	global_load_short_d16_hi v243, v68, s[12:13] offset:1536
	global_load_short_d16_hi v245, v69, s[12:13]
	global_load_ushort v247, v68, s[12:13] offset:3072
	s_add_u32 s12, s12, s18
	s_addc_u32 s13, s13, s19
	global_load_short_d16_hi v205, v68, s[12:13] offset:1536
	global_load_short_d16_hi v206, v69, s[12:13]
	global_load_ushort v180, v68, s[12:13] offset:3072
	s_add_u32 s12, s12, s18
	s_addc_u32 s13, s13, s19
	global_load_short_d16_hi v252, v68, s[12:13] offset:1536
	global_load_short_d16_hi v204, v69, s[12:13]
	global_load_ushort v179, v68, s[12:13] offset:3072
	s_add_u32 s12, s12, s18
	s_addc_u32 s13, s13, s19
	global_load_short_d16_hi v251, v68, s[12:13] offset:1536
	global_load_short_d16_hi v178, v69, s[12:13]
	global_load_ushort v208, v68, s[12:13] offset:3072
